# prompt attention V^T tile and DeltaNet scan operand tiles interleaved in LDS so each MFMA A-fragment is one ds_read_b128 instead of ds_read2_b64
# speedup vs baseline: 1.0083x; 1.0034x over previous
.LBB0_1684:
	v_readlane_b32 s0, v253, 1
	v_readlane_b32 s1, v253, 2
	s_cmp_le_i32 s0, s18
	s_cselect_b64 s[0:1], -1, 0
	s_and_b64 s[10:11], s[0:1], s[2:3]
	s_andn2_b64 vcc, exec, s[10:11]
	s_cbranch_vccnz .LBB0_1880
	v_mov_b32_e32 v10, v230
	v_mov_b32_e32 v0, v233
	v_readfirstlane_b32 s12, v2
	v_mov_b32_e32 v2, v228
	v_readfirstlane_b32 s2, v10
	v_readfirstlane_b32 s16, v2
	v_readfirstlane_b32 s0, v8
	v_readfirstlane_b32 s1, v9
	v_readfirstlane_b32 s8, v6
	v_readfirstlane_b32 s15, v7
	v_readfirstlane_b32 s9, v4
	v_readfirstlane_b32 s14, v5
	v_readfirstlane_b32 s13, v3
	s_cmp_gt_i32 s16, 31
	v_readfirstlane_b32 s17, v0
	s_cbranch_scc1 .LBB0_1690
	s_ashr_i32 s4, s2, 6
	s_add_u32 s18, s0, 0x47f76400
	s_addc_u32 s19, s1, 0
	s_add_u32 s20, s0, 0x46f76400
	s_addc_u32 s21, s1, 0
	s_add_u32 s24, s0, 0x45f76400
	s_addc_u32 s25, s1, 0
	s_add_u32 s2, s0, 0x49776400
	s_addc_u32 s3, s1, 0
	s_ashr_i32 s5, s4, 31
	s_lshl_b64 s[6:7], s[4:5], 12
	v_and_b32_e32 v0, 63, v10
	s_add_u32 s6, s0, s6
	s_addc_u32 s7, s1, s7
	v_lshlrev_b32_e32 v0, 6, v0
	v_lshl_add_u64 v[4:5], s[6:7], 0, v[0:1]
	s_mov_b64 s[6:7], 0x43f76400
	v_lshl_add_u64 v[106:107], v[4:5], 0, s[6:7]
	v_readlane_b32 s6, v253, 36
	v_and_b32_e32 v2, 15, v10
	s_lshl_b32 s28, s6, 3
	v_mov_b32_e32 v0, 0x1100
	s_movk_i32 s6, 0x110
	v_lshlrev_b32_e32 v118, 3, v10
	v_readlane_b32 s7, v253, 37
	v_mad_u32_u24 v180, v2, s6, v0
	v_mov_b32_e32 v0, 0x900
	s_movk_i32 s6, 0x90
	v_ashrrev_i32_e32 v119, 31, v118
	v_bfe_u32 v3, v10, 2, 4
	v_mad_u32_u24 v181, v2, s6, v0
	v_lshl_add_u64 v[14:15], v[118:119], 1, s[0:1]
	s_mov_b64 s[6:7], 0x48f76400
	v_and_b32_e32 v177, 12, v3
	v_or_b32_e32 v11, 3, v3
	v_or_b32_e32 v16, 19, v3
	v_or_b32_e32 v17, 35, v3
	v_or_b32_e32 v18, 51, v3
	v_lshlrev_b32_e32 v3, 9, v3
	v_lshl_add_u64 v[120:121], v[14:15], 0, s[6:7]
	v_ashrrev_i32_e32 v19, 4, v10
	s_movk_i32 s6, 0x88
	s_lshl_b32 s4, s4, 4
	v_or_b32_e32 v110, 0x8600, v3
	v_or_b32_e32 v112, 0xa600, v3
	v_or_b32_e32 v114, 0xc600, v3
	v_or_b32_e32 v116, 0xe600, v3
	v_add_u32_e32 v3, 0x200, v10
	v_mul_lo_u32 v19, v19, s6
	v_and_b32_e32 v20, 0x78, v118
	s_ashr_i32 s5, s4, 31
	v_add_lshl_u32 v182, v19, v20, 1
	v_ashrrev_i32_e32 v19, 4, v3
	v_and_b32_e32 v176, 31, v10
	s_add_u32 s30, s8, 0x4080000
	v_mul_lo_u32 v19, v19, s6
	v_lshrrev_b32_e32 v10, 3, v10
	s_movk_i32 s6, 0x48
	v_lshlrev_b32_e32 v0, 11, v177
	v_lshlrev_b32_e32 v4, 11, v11
	v_mov_b32_e32 v5, v1
	s_addc_u32 s31, s15, 0
	v_lshlrev_b32_e32 v14, 3, v3
	v_add_lshl_u32 v183, v19, v20, 1
	v_mul_lo_u32 v10, v10, s6
	v_and_b32_e32 v19, 56, v118
	v_lshrrev_b32_e32 v3, 3, v3
	s_lshl_b64 s[4:5], s[4:5], 2
	v_add_lshl_u32 v184, v10, v19, 1
	v_mul_lo_u32 v3, v3, s6
	v_lshlrev_b32_e32 v126, 9, v11
	v_lshl_add_u64 v[10:11], v[0:1], 0, s[4:5]
	v_lshlrev_b32_e32 v0, 2, v2
	s_add_u32 s6, s0, 0x369da000
	v_lshl_add_u64 v[4:5], v[4:5], 0, s[4:5]
	v_lshlrev_b32_e32 v6, 11, v16
	v_mov_b32_e32 v7, v1
	s_addc_u32 s7, s1, 0
	v_or_b32_e32 v4, v4, v0
	v_lshl_add_u64 v[154:155], s[6:7], 0, v[4:5]
	v_lshl_add_u64 v[4:5], v[6:7], 0, s[4:5]
	v_lshlrev_b32_e32 v8, 11, v17
	v_mov_b32_e32 v9, v1
	v_or_b32_e32 v4, v4, v0
	v_lshl_add_u64 v[156:157], s[6:7], 0, v[4:5]
	v_lshl_add_u64 v[4:5], v[8:9], 0, s[4:5]
	v_lshlrev_b32_e32 v12, 11, v18
	v_mov_b32_e32 v13, v1
	v_or_b32_e32 v4, v4, v0
	v_lshl_add_u64 v[158:159], s[6:7], 0, v[4:5]
	v_lshl_add_u64 v[4:5], v[12:13], 0, s[4:5]
	v_lshlrev_b32_e32 v108, 9, v177
	v_ashrrev_i32_e32 v15, 31, v14
	v_or_b32_e32 v10, v10, v0
	v_or_b32_e32 v4, v4, v0
	v_lshlrev_b32_e32 v0, 2, v229
	v_mul_u32_u24_e32 v178, 0x90, v2
	v_mul_u32_u24_e32 v179, 0x110, v2
	v_mov_b32_e32 v111, v1
	v_mov_b32_e32 v113, v1
	v_mov_b32_e32 v115, v1
	v_mov_b32_e32 v117, v1
	v_add_lshl_u32 v185, v3, v19, 1
	v_and_b32_e32 v255, 1, v230
	v_lshl_add_u32 v182, v255, 4, v182
	v_lshl_add_u32 v183, v255, 4, v183
	v_lshl_add_u32 v184, v255, 4, v184
	v_lshl_add_u32 v185, v255, 4, v185
	v_bfe_u32 v255, v230, 1, 1
	v_mul_u32_u24_e32 v255, 24, v255
	v_sub_u32_e32 v182, v182, v255
	v_sub_u32_e32 v183, v183, v255
	v_sub_u32_e32 v184, v184, v255
	v_sub_u32_e32 v185, v185, v255
	v_mov_b32_e32 v109, v1
	v_or_b32_e32 v122, 0x200, v108
	v_mov_b32_e32 v123, v1
	v_or_b32_e32 v124, 0x400, v108
	v_mov_b32_e32 v125, v1
	v_mov_b32_e32 v127, v1
	v_or_b32_e32 v128, 0x2000, v108
	v_mov_b32_e32 v129, v1
	v_or_b32_e32 v130, 0x2200, v108
	v_mov_b32_e32 v131, v1
	v_or_b32_e32 v132, 0x2400, v108
	v_mov_b32_e32 v133, v1
	v_lshlrev_b32_e32 v134, 9, v16
	v_mov_b32_e32 v135, v1
	v_or_b32_e32 v136, 0x4000, v108
	v_mov_b32_e32 v137, v1
	v_or_b32_e32 v138, 0x4200, v108
	v_mov_b32_e32 v139, v1
	v_or_b32_e32 v140, 0x4400, v108
	v_mov_b32_e32 v141, v1
	v_lshlrev_b32_e32 v142, 9, v17
	v_mov_b32_e32 v143, v1
	v_or_b32_e32 v144, 0x6000, v108
	v_mov_b32_e32 v145, v1
	v_or_b32_e32 v146, 0x6200, v108
	v_mov_b32_e32 v147, v1
	v_or_b32_e32 v148, 0x6400, v108
	v_mov_b32_e32 v149, v1
	v_lshlrev_b32_e32 v150, 9, v18
	v_mov_b32_e32 v151, v1
	v_lshl_add_u64 v[152:153], s[0:1], 0, v[10:11]
	v_lshl_add_u64 v[160:161], s[6:7], 0, v[4:5]
	s_lshl_b32 s34, s16, 5
	s_lshl_b32 s35, s17, 5
	v_and_b32_e32 v186, 0x100, v0
	v_lshlrev_b32_e32 v0, 2, v2
	v_lshlrev_b64 v[162:163], 1, v[14:15]
	s_mov_b32 s36, s16
.LBB0_1687:
	s_and_b32 s6, s16, 3
	s_lshl_b32 s44, s6, 9
	s_lshl_b32 s6, s36, 5
	s_ashr_i32 s7, s6, 31
	s_ashr_i32 s37, s36, 2
	s_lshl_b64 s[38:39], s[6:7], 14
	s_add_u32 s40, s18, s38
	s_addc_u32 s41, s19, s39
	s_lshl_b64 s[42:43], s[6:7], 13
	v_lshl_add_u64 v[26:27], v[120:121], 0, s[42:43]
	s_add_u32 s42, s20, s38
	s_addc_u32 s43, s21, s39
	s_add_u32 s38, s24, s38
	v_or_b32_e32 v30, s6, v176
	s_addc_u32 s39, s25, s39
	v_lshlrev_b64 v[164:165], 1, v[118:119]
	v_ashrrev_i32_e32 v31, 31, v30
	v_lshl_add_u64 v[2:3], s[38:39], 0, v[164:165]
	v_lshl_add_u64 v[6:7], s[38:39], 0, v[162:163]
	v_lshl_add_u64 v[10:11], s[42:43], 0, v[164:165]
	v_lshl_add_u64 v[14:15], s[42:43], 0, v[162:163]
	v_lshl_add_u64 v[18:19], s[40:41], 0, v[164:165]
	v_lshl_add_u64 v[22:23], s[40:41], 0, v[162:163]
	v_lshl_add_u64 v[30:31], v[30:31], 2, s[2:3]
	s_lshl_b64 s[6:7], s[6:7], 15
	s_waitcnt vmcnt(0) lgkmcnt(0)
	s_barrier
	global_load_dwordx4 v[2:5], v[2:3], off
	s_mov_b32 s38, 0
	global_load_dwordx4 v[6:9], v[6:7], off
	v_mov_b32_e32 v188, v186
	global_load_dwordx4 v[10:13], v[10:11], off
	s_nop 0
	global_load_dwordx4 v[14:17], v[14:15], off
	s_nop 0
	global_load_dwordx4 v[18:21], v[18:19], off
	s_nop 0
	global_load_dwordx4 v[22:25], v[22:23], off
	s_nop 0
	global_load_dwordx4 v[26:29], v[26:27], off
	s_nop 0
	global_load_dword v187, v[30:31], off
	v_lshl_add_u64 v[30:31], v[106:107], 0, s[6:7]
	global_load_dwordx4 v[78:81], v[30:31], off offset:48
	global_load_dwordx4 v[82:85], v[30:31], off offset:32
	global_load_dwordx4 v[86:89], v[30:31], off offset:16
	global_load_dwordx4 v[90:93], v[30:31], off
	s_lshl_b32 s6, s37, 11
	v_add_u32_e32 v30, 0, v182
	s_ashr_i32 s7, s6, 31
	s_lshl_b64 s[6:7], s[6:7], 11
	s_or_b32 s6, s6, s44
	v_lshl_add_u64 v[166:167], v[152:153], 0, s[6:7]
	v_lshl_add_u64 v[168:169], v[154:155], 0, s[6:7]
	v_lshl_add_u64 v[170:171], v[156:157], 0, s[6:7]
	v_lshl_add_u64 v[172:173], v[158:159], 0, s[6:7]
	v_lshl_add_u64 v[174:175], v[160:161], 0, s[6:7]
	s_mov_b64 s[6:7], 0
	s_waitcnt vmcnt(11)
	ds_write_b64 v30, v[2:3]
	ds_write_b64 v30, v[4:5] offset:16
	v_add_u32_e32 v2, 0, v183
	s_waitcnt vmcnt(10)
	ds_write_b64 v2, v[6:7]
	ds_write_b64 v2, v[8:9] offset:16
	s_waitcnt vmcnt(9)
	ds_write_b64 v30, v[10:11] offset:17408
	ds_write_b64 v30, v[12:13] offset:17424
	s_waitcnt vmcnt(8)
	ds_write_b64 v2, v[14:15] offset:17408
	ds_write_b64 v2, v[16:17] offset:17424
	v_add_u32_e32 v2, 0, v184
	v_add_u32_e32 v3, 0, v185
	v_mov_b32_e32 v6, 0
	s_waitcnt vmcnt(7)
	ds_write_b64 v2, v[18:19] offset:34816
	ds_write_b64 v2, v[20:21] offset:34832
	s_waitcnt vmcnt(6)
	ds_write_b64 v3, v[22:23] offset:34816
	ds_write_b64 v3, v[24:25] offset:34832
	s_waitcnt vmcnt(5)
	ds_write_b64 v2, v[26:27] offset:53248
	ds_write_b64 v2, v[28:29] offset:53264
	v_mov_b32_e32 v7, v6
	v_mov_b32_e32 v8, v6
	v_mov_b32_e32 v9, v6
	v_mov_b32_e32 v18, v6
	v_mov_b32_e32 v19, v6
	v_mov_b32_e32 v20, v6
	v_mov_b32_e32 v21, v6
	v_mov_b32_e32 v10, v6
	v_mov_b32_e32 v11, v6
	v_mov_b32_e32 v12, v6
	v_mov_b32_e32 v13, v6
	v_mov_b32_e32 v2, v6
	v_mov_b32_e32 v3, v6
	v_mov_b32_e32 v4, v6
	v_mov_b32_e32 v5, v6
	v_mov_b32_e32 v22, v6
	v_mov_b32_e32 v23, v6
	v_mov_b32_e32 v24, v6
	v_mov_b32_e32 v25, v6
	v_mov_b32_e32 v14, v6
	v_mov_b32_e32 v15, v6
	v_mov_b32_e32 v16, v6
	v_mov_b32_e32 v17, v6
	v_mov_b32_e32 v30, v6
	v_mov_b32_e32 v31, v6
	v_mov_b32_e32 v32, v6
	v_mov_b32_e32 v33, v6
	v_mov_b32_e32 v26, v6
	v_mov_b32_e32 v27, v6
	v_mov_b32_e32 v28, v6
	v_mov_b32_e32 v29, v6
	s_waitcnt lgkmcnt(0)
	s_barrier
.LBB0_1688:
	s_bitcmp1_b32 s38, 0
	s_cselect_b32 s39, 0xf400, 0
	s_add_i32 s39, s39, 0
	s_cmp_lg_u32 s6, 0x3e0000
	s_cselect_b64 s[40:41], -1, 0
	s_cmp_lg_u64 s[40:41], 0
	s_addc_u32 s40, s34, s38
	s_ashr_i32 s41, s40, 31
	s_lshl_b64 s[42:43], s[40:41], 14
	s_add_u32 s44, s18, s42
	s_addc_u32 s45, s19, s43
	s_lshl_b64 s[46:47], s[40:41], 13
	v_lshl_add_u64 v[34:35], v[120:121], 0, s[46:47]
	s_add_u32 s46, s20, s42
	s_addc_u32 s47, s21, s43
	s_add_u32 s42, s24, s42
	s_addc_u32 s43, s25, s43
	v_lshl_add_u64 v[38:39], s[42:43], 0, v[162:163]
	v_lshl_add_u64 v[40:41], s[46:47], 0, v[164:165]
	s_lshl_b64 s[40:41], s[40:41], 15
	v_lshl_add_u64 v[36:37], s[42:43], 0, v[164:165]
	global_load_dwordx4 v[50:53], v[38:39], off
	global_load_dwordx4 v[54:57], v[40:41], off
	v_lshl_add_u64 v[38:39], s[46:47], 0, v[162:163]
	v_lshl_add_u64 v[40:41], s[44:45], 0, v[164:165]
	v_lshl_add_u64 v[46:47], s[44:45], 0, v[162:163]
	v_lshl_add_u64 v[48:49], v[106:107], 0, s[40:41]
	global_load_dwordx4 v[62:65], v[38:39], off
	global_load_dwordx4 v[58:61], v[40:41], off
	global_load_dwordx4 v[70:73], v[36:37], off
	global_load_dwordx4 v[66:69], v[34:35], off
	s_nop 0
	global_load_dwordx4 v[34:37], v[48:49], off offset:48
	global_load_dwordx4 v[38:41], v[48:49], off offset:32
	global_load_dwordx4 v[42:45], v[48:49], off offset:16
	global_load_dwordx4 v[74:77], v[46:47], off
	s_nop 0
	global_load_dwordx4 v[46:49], v[48:49], off
	v_lshlrev_b32_e32 v189, 2, v177
	v_add3_u32 v226, s39, v179, v189
	v_add3_u32 v227, s39, v180, v189
	ds_read_b128 v[190:193], v226
	ds_read_b128 v[194:197], v226 offset:64
	ds_read_b128 v[198:201], v226 offset:128
	ds_read_b128 v[202:205], v226 offset:192
	ds_read_b128 v[206:209], v227
	ds_read_b128 v[210:213], v227 offset:64
	ds_read_b128 v[214:217], v227 offset:128
	ds_read_b128 v[218:221], v227 offset:192
	v_cvt_pk_bf16_f32 v94, v18, v19
	v_cvt_pk_bf16_f32 v95, v20, v21
	v_cvt_pk_bf16_f32 v96, v6, v7
	v_cvt_pk_bf16_f32 v97, v8, v9
	v_cvt_pk_bf16_f32 v98, v10, v11
	v_cvt_pk_bf16_f32 v99, v12, v13
	v_cvt_pk_bf16_f32 v100, v2, v3
	v_cvt_pk_bf16_f32 v101, v4, v5
	v_cvt_pk_bf16_f32 v102, v22, v23
	v_cvt_pk_bf16_f32 v103, v24, v25
	v_cvt_pk_bf16_f32 v104, v14, v15
	v_cvt_pk_bf16_f32 v105, v16, v17
	v_cvt_pk_bf16_f32 v222, v30, v31
	v_cvt_pk_bf16_f32 v223, v32, v33
	v_cvt_pk_bf16_f32 v224, v26, v27
	v_cvt_pk_bf16_f32 v225, v28, v29
	s_waitcnt vmcnt(11) lgkmcnt(7)
	v_mfma_f32_16x16x32_bf16 v[90:93], v[190:193], v[94:97], v[90:93]
	s_waitcnt lgkmcnt(3)
	v_mfma_f32_16x16x32_bf16 v[86:89], v[206:209], v[94:97], v[86:89]
	v_mfma_f32_16x16x32_bf16 v[90:93], v[194:197], v[98:101], v[90:93]
	s_waitcnt lgkmcnt(2)
	v_mfma_f32_16x16x32_bf16 v[86:89], v[210:213], v[98:101], v[86:89]
	v_mfma_f32_16x16x32_bf16 v[90:93], v[198:201], v[102:105], v[90:93]
	s_waitcnt lgkmcnt(1)
	v_mfma_f32_16x16x32_bf16 v[86:89], v[214:217], v[102:105], v[86:89]
	v_mfma_f32_16x16x32_bf16 v[90:93], v[202:205], v[222:225], v[90:93]
	s_waitcnt lgkmcnt(0)
	v_mfma_f32_16x16x32_bf16 v[190:193], v[218:221], v[222:225], v[86:89]
	v_add_u32_e32 v202, 0x2000, v226
	v_add_u32_e32 v218, 0x3000, v226
	s_nop 2
	ds_read_b128 v[86:89], v202 offset:512
	ds_read_b128 v[194:197], v202 offset:576
	ds_read_b128 v[198:201], v202 offset:640
	ds_read_b128 v[202:205], v202 offset:704
	ds_read_b128 v[206:209], v218 offset:768
	ds_read_b128 v[210:213], v218 offset:832
	ds_read_b128 v[214:217], v218 offset:896
	ds_read_b128 v[218:221], v218 offset:960
	s_waitcnt lgkmcnt(7)
	v_mfma_f32_16x16x32_bf16 v[82:85], v[86:89], v[94:97], v[82:85]
	s_waitcnt lgkmcnt(3)
	v_mfma_f32_16x16x32_bf16 v[78:81], v[206:209], v[94:97], v[78:81]
	v_mfma_f32_16x16x32_bf16 v[82:85], v[194:197], v[98:101], v[82:85]
	s_waitcnt lgkmcnt(2)
	v_mfma_f32_16x16x32_bf16 v[78:81], v[210:213], v[98:101], v[78:81]
	v_mfma_f32_16x16x32_bf16 v[82:85], v[198:201], v[102:105], v[82:85]
	s_waitcnt lgkmcnt(1)
	v_mfma_f32_16x16x32_bf16 v[78:81], v[214:217], v[102:105], v[78:81]
	v_mfma_f32_16x16x32_bf16 v[82:85], v[202:205], v[222:225], v[82:85]
	s_waitcnt lgkmcnt(0)
	v_mfma_f32_16x16x32_bf16 v[78:81], v[218:221], v[222:225], v[78:81]
	v_add_u32_e32 v202, 0x4000, v226
	v_add_u32_e32 v218, 0x4000, v227
	ds_read_b128 v[86:89], v202 offset:1024
	ds_read_b128 v[194:197], v202 offset:1088
	ds_read_b128 v[198:201], v202 offset:1152
	ds_read_b128 v[202:205], v202 offset:1216
	ds_read_b128 v[206:209], v218 offset:1024
	ds_read_b128 v[210:213], v218 offset:1088
	ds_read_b128 v[214:217], v218 offset:1152
	ds_read_b128 v[218:221], v218 offset:1216
	s_waitcnt lgkmcnt(7)
	v_mfma_f32_16x16x32_bf16 v[86:89], v[86:89], v[94:97], 0
	s_waitcnt lgkmcnt(3)
	v_mfma_f32_16x16x32_bf16 v[206:209], v[206:209], v[94:97], 0
	v_mfma_f32_16x16x32_bf16 v[86:89], v[194:197], v[98:101], v[86:89]
	s_waitcnt lgkmcnt(2)
	v_mfma_f32_16x16x32_bf16 v[194:197], v[210:213], v[98:101], v[206:209]
	v_mfma_f32_16x16x32_bf16 v[86:89], v[198:201], v[102:105], v[86:89]
	s_waitcnt lgkmcnt(1)
	v_mfma_f32_16x16x32_bf16 v[194:197], v[214:217], v[102:105], v[194:197]
	v_mfma_f32_16x16x32_bf16 v[198:201], v[202:205], v[222:225], v[86:89]
	s_waitcnt lgkmcnt(0)
	v_mfma_f32_16x16x32_bf16 v[194:197], v[218:221], v[222:225], v[194:197]
	v_add_u32_e32 v210, 0x6000, v226
	v_add_u32_e32 v226, 0x7000, v226
	s_nop 0
	ds_read_b128 v[86:89], v210 offset:1536
	ds_read_b128 v[202:205], v210 offset:1600
	ds_read_b128 v[206:209], v210 offset:1664
	ds_read_b128 v[210:213], v210 offset:1728
	ds_read_b128 v[214:217], v226 offset:1792
	ds_read_b128 v[218:221], v226 offset:1856
	ds_read_b128 v[238:241], v226 offset:1920
	ds_read_b128 v[242:245], v226 offset:1984
	s_waitcnt lgkmcnt(7)
	v_mfma_f32_16x16x32_bf16 v[86:89], v[86:89], v[94:97], 0
	s_waitcnt lgkmcnt(3)
	v_mfma_f32_16x16x32_bf16 v[94:97], v[214:217], v[94:97], 0
	v_mfma_f32_16x16x32_bf16 v[86:89], v[202:205], v[98:101], v[86:89]
	s_waitcnt lgkmcnt(2)
	v_mfma_f32_16x16x32_bf16 v[94:97], v[218:221], v[98:101], v[94:97]
	v_mfma_f32_16x16x32_bf16 v[86:89], v[206:209], v[102:105], v[86:89]
	s_waitcnt lgkmcnt(1)
	v_mfma_f32_16x16x32_bf16 v[94:97], v[238:241], v[102:105], v[94:97]
	v_mfma_f32_16x16x32_bf16 v[102:105], v[210:213], v[222:225], v[86:89]
	s_waitcnt lgkmcnt(0)
	v_mfma_f32_16x16x32_bf16 v[202:205], v[242:245], v[222:225], v[94:97]
	v_add3_u32 v219, s39, v178, v189
	v_cvt_pk_bf16_f32 v86, v90, v91
	v_cvt_pk_bf16_f32 v87, v92, v93
	v_cvt_pk_bf16_f32 v90, v82, v83
	v_cvt_pk_bf16_f32 v92, v78, v79
	v_add_u32_e32 v78, 0xd000, v219
	v_add_u32_e32 v82, 0xd800, v219
	s_nop 1
	v_add_u32_e32 v94, 0xe000, v219
	v_cvt_pk_bf16_f32 v88, v190, v191
	v_cvt_pk_bf16_f32 v89, v192, v193
	v_cvt_pk_bf16_f32 v91, v84, v85
	v_cvt_pk_bf16_f32 v93, v80, v81
	ds_read_b128 v[78:81], v78
	ds_read_b128 v[82:85], v82 offset:256
	ds_read_b128 v[190:193], v94 offset:512
	ds_read_b128 v[206:209], v94 offset:576
	v_add_u32_e32 v94, 0xe800, v219
	ds_read_b128 v[210:213], v94 offset:768
	ds_read_b128 v[214:217], v94 offset:832
	ds_bpermute_b32 v218, v188, v187
	s_waitcnt lgkmcnt(6)
	v_mfma_f32_16x16x32_bf16 v[98:101], v[78:81], v[86:89], v[198:201]
	s_waitcnt lgkmcnt(4)
	v_mfma_f32_16x16x32_bf16 v[78:81], v[190:193], v[86:89], v[102:105]
	s_waitcnt lgkmcnt(2)
	v_mfma_f32_16x16x32_bf16 v[102:105], v[210:213], v[86:89], v[202:205]
	v_mfma_f32_16x16x32_bf16 v[94:97], v[82:85], v[86:89], v[194:197]
	v_mfma_f32_16x16x32_bf16 v[82:85], v[206:209], v[90:93], v[78:81]
	s_waitcnt lgkmcnt(1)
	v_mfma_f32_16x16x32_bf16 v[78:81], v[214:217], v[90:93], v[102:105]
	v_add3_u32 v189, s39, v181, v189
	v_add_u32_e32 v190, 0x8800, v219
	v_add_u32_e32 v189, 0x8800, v189
	s_nop 0
	ds_read_b128 v[102:105], v190
	ds_read_b128 v[190:193], v190 offset:64
	ds_read_b128 v[194:197], v189
	ds_read_b128 v[198:201], v189 offset:64
	v_add_u32_e32 v189, 0x9800, v219
	ds_read_b128 v[202:205], v189 offset:512
	ds_read_b128 v[206:209], v189 offset:576
	v_add_u32_e32 v189, 0xa000, v219
	ds_read_b128 v[210:213], v189 offset:768
	ds_read_b128 v[214:217], v189 offset:832
	s_waitcnt lgkmcnt(8)
	v_pk_mul_f32 v[20:21], v[20:21], v[218:219] op_sel_hi:[1,0]
	v_pk_mul_f32 v[18:19], v[18:19], v[218:219] op_sel_hi:[1,0]
	v_pk_mul_f32 v[8:9], v[8:9], v[218:219] op_sel_hi:[1,0]
	v_pk_mul_f32 v[6:7], v[6:7], v[218:219] op_sel_hi:[1,0]
	v_pk_mul_f32 v[12:13], v[12:13], v[218:219] op_sel_hi:[1,0]
	v_pk_mul_f32 v[10:11], v[10:11], v[218:219] op_sel_hi:[1,0]
	v_pk_mul_f32 v[4:5], v[4:5], v[218:219] op_sel_hi:[1,0]
	v_pk_mul_f32 v[2:3], v[2:3], v[218:219] op_sel_hi:[1,0]
	v_pk_mul_f32 v[24:25], v[24:25], v[218:219] op_sel_hi:[1,0]
	v_pk_mul_f32 v[22:23], v[22:23], v[218:219] op_sel_hi:[1,0]
	v_pk_mul_f32 v[16:17], v[16:17], v[218:219] op_sel_hi:[1,0]
	v_pk_mul_f32 v[14:15], v[14:15], v[218:219] op_sel_hi:[1,0]
	v_pk_mul_f32 v[32:33], v[32:33], v[218:219] op_sel_hi:[1,0]
	v_pk_mul_f32 v[30:31], v[30:31], v[218:219] op_sel_hi:[1,0]
	v_pk_mul_f32 v[28:29], v[28:29], v[218:219] op_sel_hi:[1,0]
	v_pk_mul_f32 v[26:27], v[26:27], v[218:219] op_sel_hi:[1,0]
	s_waitcnt lgkmcnt(7)
	v_mfma_f32_16x16x32_bf16 v[18:21], v[102:105], v[86:89], v[18:21]
	s_waitcnt lgkmcnt(5)
	v_mfma_f32_16x16x32_bf16 v[6:9], v[194:197], v[86:89], v[6:9]
	s_waitcnt lgkmcnt(3)
	v_mfma_f32_16x16x32_bf16 v[10:13], v[202:205], v[86:89], v[10:13]
	s_waitcnt lgkmcnt(1)
	v_mfma_f32_16x16x32_bf16 v[2:5], v[210:213], v[86:89], v[2:5]
	v_mfma_f32_16x16x32_bf16 v[18:21], v[190:193], v[90:93], v[18:21]
	v_mfma_f32_16x16x32_bf16 v[6:9], v[198:201], v[90:93], v[6:9]
	v_mfma_f32_16x16x32_bf16 v[10:13], v[206:209], v[90:93], v[10:13]
	s_waitcnt lgkmcnt(0)
	v_mfma_f32_16x16x32_bf16 v[2:5], v[214:217], v[90:93], v[2:5]
	v_add_u32_e32 v189, 0xa800, v219
	ds_read_b128 v[102:105], v189 offset:1024
	ds_read_b128 v[190:193], v189 offset:1088
	v_add_u32_e32 v189, 0xb000, v219
	ds_read_b128 v[194:197], v189 offset:1280
	ds_read_b128 v[198:201], v189 offset:1344
	v_add_u32_e32 v189, 0xb800, v219
	ds_read_b128 v[202:205], v189 offset:1536
	ds_read_b128 v[206:209], v189 offset:1600
	v_add_u32_e32 v189, 0xc000, v219
	ds_read_b128 v[210:213], v189 offset:1792
	ds_read_b128 v[214:217], v189 offset:1856
	s_waitcnt lgkmcnt(7)
	v_mfma_f32_16x16x32_bf16 v[22:25], v[102:105], v[86:89], v[22:25]
	s_waitcnt lgkmcnt(5)
	v_mfma_f32_16x16x32_bf16 v[14:17], v[194:197], v[86:89], v[14:17]
	s_waitcnt lgkmcnt(3)
	v_mfma_f32_16x16x32_bf16 v[30:33], v[202:205], v[86:89], v[30:33]
	s_waitcnt lgkmcnt(1)
	v_mfma_f32_16x16x32_bf16 v[26:29], v[210:213], v[86:89], v[26:29]
	v_mfma_f32_16x16x32_bf16 v[22:25], v[190:193], v[90:93], v[22:25]
	v_mfma_f32_16x16x32_bf16 v[14:17], v[198:201], v[90:93], v[14:17]
	v_mfma_f32_16x16x32_bf16 v[30:33], v[206:209], v[90:93], v[30:33]
	s_waitcnt lgkmcnt(0)
	v_mfma_f32_16x16x32_bf16 v[26:29], v[214:217], v[90:93], v[26:29]
	v_lshl_add_u64 v[86:87], v[166:167], 0, s[6:7]
	s_mov_b32 s39, 0x369da000
	v_add_co_u32_e32 v88, vcc, s39, v86
	s_mov_b32 s39, 0x369db000
	s_nop 0
	v_addc_co_u32_e32 v89, vcc, 0, v87, vcc
	v_add_co_u32_e32 v90, vcc, s39, v86
	s_mov_b32 s39, 0x369e2000
	s_nop 0
	v_addc_co_u32_e32 v91, vcc, 0, v87, vcc
	global_store_dword v[90:91], v98, off offset:-4096
	global_store_dword v[88:89], v99, off offset:2048
	global_store_dword v[90:91], v100, off
	v_lshl_add_u64 v[88:89], v[168:169], 0, s[6:7]
	global_store_dword v[88:89], v101, off
	v_add_co_u32_e32 v88, vcc, s39, v86
	s_mov_b32 s39, 0x369e3000
	s_nop 0
	v_addc_co_u32_e32 v89, vcc, 0, v87, vcc
	v_add_co_u32_e32 v90, vcc, s39, v86
	s_mov_b32 s39, 0x369ea000
	s_nop 0
	v_addc_co_u32_e32 v91, vcc, 0, v87, vcc
	global_store_dword v[90:91], v94, off offset:-4096
	global_store_dword v[88:89], v95, off offset:2048
	global_store_dword v[90:91], v96, off
	v_lshl_add_u64 v[88:89], v[170:171], 0, s[6:7]
	global_store_dword v[88:89], v97, off
	v_add_co_u32_e32 v88, vcc, s39, v86
	s_mov_b32 s39, 0x369eb000
	s_nop 0
	v_addc_co_u32_e32 v89, vcc, 0, v87, vcc
	v_add_co_u32_e32 v90, vcc, s39, v86
	s_mov_b32 s39, 0x369f2000
	s_nop 0
	v_addc_co_u32_e32 v91, vcc, 0, v87, vcc
	global_store_dword v[90:91], v82, off offset:-4096
	global_store_dword v[88:89], v83, off offset:2048
	global_store_dword v[90:91], v84, off
	v_lshl_add_u64 v[82:83], v[172:173], 0, s[6:7]
	global_store_dword v[82:83], v85, off
	v_add_co_u32_e32 v82, vcc, s39, v86
	s_mov_b32 s39, 0x369f3000
	s_nop 0
	v_addc_co_u32_e32 v83, vcc, 0, v87, vcc
	v_add_co_u32_e32 v84, vcc, s39, v86
	s_andn2_b32 s39, 1, s38
	s_nop 0
	v_addc_co_u32_e32 v85, vcc, 0, v87, vcc
	s_mul_i32 s39, s39, 0xf400
	global_store_dword v[84:85], v78, off offset:-4096
	global_store_dword v[82:83], v79, off offset:2048
	global_store_dword v[84:85], v80, off
	v_lshl_add_u64 v[78:79], v[174:175], 0, s[6:7]
	s_add_i32 s39, s39, 0
	global_store_dword v[78:79], v81, off
	v_add_u32_e32 v78, s39, v182
	s_add_i32 s38, s38, 1
	s_waitcnt vmcnt(22)
	ds_write_b64 v78, v[70:71]
	ds_write_b64 v78, v[72:73] offset:16
	v_add_u32_e32 v70, s39, v183
	s_add_u32 s6, s6, 0x20000
	ds_write_b64 v70, v[50:51]
	ds_write_b64 v70, v[52:53] offset:16
	ds_write_b64 v78, v[54:55] offset:17408
	ds_write_b64 v78, v[56:57] offset:17424
	ds_write_b64 v70, v[62:63] offset:17408
	ds_write_b64 v70, v[64:65] offset:17424
	s_addc_u32 s7, s7, 0
	s_waitcnt vmcnt(20)
	v_mov_b64_e32 v[80:81], v[36:37]
	s_waitcnt vmcnt(19)
	v_mov_b64_e32 v[84:85], v[40:41]
	s_waitcnt vmcnt(18)
	v_mov_b64_e32 v[88:89], v[44:45]
	s_waitcnt vmcnt(16)
	v_mov_b64_e32 v[92:93], v[48:49]
	v_add_u32_e32 v50, s39, v184
	v_add_u32_e32 v51, s39, v185
	v_add_u32_e32 v188, 4, v188
	s_cmp_eq_u32 s6, 0x400000
	v_mov_b64_e32 v[78:79], v[34:35]
	v_mov_b64_e32 v[82:83], v[38:39]
	v_mov_b64_e32 v[86:87], v[42:43]
	v_mov_b64_e32 v[90:91], v[46:47]
	ds_write_b64 v50, v[58:59] offset:34816
	ds_write_b64 v50, v[60:61] offset:34832
	ds_write_b64 v51, v[74:75] offset:34816
	ds_write_b64 v51, v[76:77] offset:34832
	ds_write_b64 v50, v[66:67] offset:53248
	ds_write_b64 v50, v[68:69] offset:53264
	s_waitcnt lgkmcnt(0)
	s_barrier
	s_cbranch_scc0 .LBB0_1688
	s_and_b32 s38, s36, 3
	s_ashr_i32 s7, s37, 31
	s_add_u32 s6, s37, s28
	s_addc_u32 s7, s7, 0
	s_lshl_b64 s[6:7], s[6:7], 18
	s_add_u32 s6, s30, s6
	s_addc_u32 s7, s31, s7
	s_lshl_b32 s37, s38, 16
	s_add_u32 s6, s6, s37
	s_addc_u32 s7, s7, 0
	s_add_u32 s6, s6, s4
	s_addc_u32 s7, s7, s5
	v_lshl_add_u64 v[34:35], s[6:7], 0, v[0:1]
	v_lshl_add_u64 v[36:37], v[34:35], 0, v[108:109]
	v_lshl_add_u64 v[38:39], v[34:35], 0, v[122:123]
	global_store_dword v[36:37], v18, off
	global_store_dword v[38:39], v19, off
	v_lshl_add_u64 v[18:19], v[34:35], 0, v[124:125]
	global_store_dword v[18:19], v20, off
	v_lshl_add_u64 v[18:19], v[34:35], 0, v[126:127]
	global_store_dword v[18:19], v21, off
	v_lshl_add_u64 v[18:19], v[34:35], 0, v[128:129]
	global_store_dword v[18:19], v6, off
	v_lshl_add_u64 v[18:19], v[34:35], 0, v[130:131]
	global_store_dword v[18:19], v7, off
	v_lshl_add_u64 v[6:7], v[34:35], 0, v[132:133]
	global_store_dword v[6:7], v8, off
	v_lshl_add_u64 v[6:7], v[34:35], 0, v[134:135]
	global_store_dword v[6:7], v9, off
	v_lshl_add_u64 v[6:7], v[34:35], 0, v[136:137]
	global_store_dword v[6:7], v10, off
	v_lshl_add_u64 v[6:7], v[34:35], 0, v[138:139]
	global_store_dword v[6:7], v11, off
	v_lshl_add_u64 v[6:7], v[34:35], 0, v[140:141]
	global_store_dword v[6:7], v12, off
	v_lshl_add_u64 v[6:7], v[34:35], 0, v[142:143]
	global_store_dword v[6:7], v13, off
	v_lshl_add_u64 v[6:7], v[34:35], 0, v[144:145]
	global_store_dword v[6:7], v2, off
	v_lshl_add_u64 v[6:7], v[34:35], 0, v[146:147]
	global_store_dword v[6:7], v3, off
	v_lshl_add_u64 v[2:3], v[34:35], 0, v[148:149]
	global_store_dword v[2:3], v4, off
	v_lshl_add_u64 v[2:3], v[34:35], 0, v[150:151]
	s_mov_b32 s6, 0x8000
	global_store_dword v[2:3], v5, off
	v_add_co_u32_e32 v2, vcc, s6, v36
	s_mov_b32 s6, 0xa000
	s_nop 0
	v_addc_co_u32_e32 v3, vcc, 0, v37, vcc
	global_store_dword v[2:3], v22, off
	global_store_dword v[2:3], v23, off offset:512
	global_store_dword v[2:3], v24, off offset:1024
	v_lshl_add_u64 v[2:3], v[34:35], 0, v[110:111]
	global_store_dword v[2:3], v25, off
	v_add_co_u32_e32 v2, vcc, s6, v36
	s_mov_b32 s6, 0xc000
	s_nop 0
	v_addc_co_u32_e32 v3, vcc, 0, v37, vcc
	global_store_dword v[2:3], v14, off
	global_store_dword v[2:3], v15, off offset:512
	global_store_dword v[2:3], v16, off offset:1024
	v_lshl_add_u64 v[2:3], v[34:35], 0, v[112:113]
	global_store_dword v[2:3], v17, off
	v_add_co_u32_e32 v2, vcc, s6, v36
	s_add_i32 s36, s36, s17
	s_nop 0
	v_addc_co_u32_e32 v3, vcc, 0, v37, vcc
	global_store_dword v[2:3], v30, off
	global_store_dword v[2:3], v31, off offset:512
	global_store_dword v[2:3], v32, off offset:1024
	v_lshl_add_u64 v[2:3], v[34:35], 0, v[114:115]
	global_store_dword v[2:3], v33, off
	v_add_co_u32_e32 v2, vcc, 0xe000, v36
	s_add_i32 s16, s16, s17
	s_nop 0
	v_addc_co_u32_e32 v3, vcc, 0, v37, vcc
	s_add_i32 s34, s34, s35
	global_store_dword v[2:3], v26, off
	global_store_dword v[2:3], v27, off offset:512
	global_store_dword v[2:3], v28, off offset:1024
	v_lshl_add_u64 v[2:3], v[34:35], 0, v[116:117]
	s_cmp_gt_i32 s36, 31
	global_store_dword v[2:3], v29, off
	s_cbranch_scc0 .LBB0_1687

.LBB0_1741:
	v_mov_b32_e32 v4, s45
	v_mov_b32_e32 v0, v230
	v_mov_b32_e32 v5, s24
	s_waitcnt lgkmcnt(0)
	s_barrier
	v_mov_b32_e32 v3, s7
	v_readfirstlane_b32 s13, v4
	v_mov_b32_e32 v4, s6
	v_mov_b32_e32 v2, s9
	v_readfirstlane_b32 s36, v3
	v_mov_b32_e32 v3, s8
	v_readfirstlane_b32 s2, v0
	v_readfirstlane_b32 s24, v3
	v_readfirstlane_b32 s34, v2
	v_mov_b32_e32 v2, s25
	v_mov_b32_e32 v3, s44
	v_readfirstlane_b32 s12, v5
	v_readfirstlane_b32 s25, v2
	v_mov_b32_e32 v2, v233
	v_readfirstlane_b32 s35, v4
	v_readfirstlane_b32 s3, v2
	v_mov_b32_e32 v2, v228
	v_readfirstlane_b32 s38, v3
	v_readfirstlane_b32 s6, v2
	s_sub_i32 s7, s6, 32
	s_cmp_gt_i32 s3, 64
	s_cselect_b64 s[0:1], -1, 0
	s_and_b64 s[4:5], s[0:1], exec
	s_cselect_b32 s37, s7, s6
	s_cmp_lt_i32 s37, 0
	s_cbranch_scc1 .LBB0_1796
	s_cmpk_gt_u32 s37, 0x3ff
	s_cbranch_scc1 .LBB0_1796
	s_sub_i32 s4, s3, 32
	s_and_b64 s[0:1], s[0:1], exec
	v_and_b32_e32 v2, 15, v0
	v_bfe_u32 v5, v0, 4, 2
	v_and_b32_e32 v3, 48, v0
	s_cselect_b32 s39, s4, s3
	s_not_b32 s0, s37
	v_add_u32_e32 v75, 0, v3
	v_mul_u32_u24_e32 v77, 0xd0, v2
	v_mul_u32_u24_e32 v2, 0x90, v2
	v_lshlrev_b32_e32 v3, 4, v5
	v_lshlrev_b32_e32 v4, 3, v0
	s_add_i32 s40, s39, s0
	v_add3_u32 v94, 0, v2, v3
	v_ashrrev_i32_e32 v2, 3, v0
	s_movk_i32 s4, 0x90
	v_and_b32_e32 v76, 56, v4
	s_add_u32 s41, s12, 0x341aa000
	v_mul_lo_u32 v3, v2, s4
	v_lshlrev_b32_e32 v4, 1, v76
	s_addc_u32 s42, s13, 0
	v_add3_u32 v98, 0, v3, v4
	v_and_b32_e32 v74, 1, v0
	v_lshl_add_u32 v98, v74, 4, v98
	v_bfe_u32 v74, v0, 1, 1
	v_mul_u32_u24_e32 v74, 24, v74
	v_sub_u32_e32 v98, v98, v74
	v_ashrrev_i32_e32 v3, 31, v2
	s_mov_b32 s5, 0x2aaaaaab
	s_add_u32 s8, s12, 0x359da000
	v_lshlrev_b64 v[78:79], 12, v[2:3]
	v_mul_hi_i32 v2, v0, s5
	s_addc_u32 s9, s13, 0
	v_lshrrev_b32_e32 v3, 31, v2
	v_ashrrev_i32_e32 v2, 1, v2
	s_add_u32 s43, s12, 0x2a512000
	v_add_u32_e32 v6, v2, v3
	s_movk_i32 s4, 0xd0
	s_addc_u32 s44, s13, 0
	s_ashr_i32 s0, s2, 2
	v_mul_lo_u32 v2, v6, s4
	s_and_b32 s45, s0, -16
	v_bfi_b32 v72, -16, s0, v0
	s_movk_i32 s0, 0x300
	s_movk_i32 s2, 0x100
	v_add_u32_e32 v99, 0, v2
	v_mul_lo_u32 v2, v6, 12
	v_cmp_gt_i32_e64 s[0:1], s0, v0
	v_cmp_gt_i32_e64 s[2:3], s2, v0
	v_sub_u32_e32 v2, v0, v2
	v_add_u32_e32 v0, 0x200, v0
	v_mul_hi_i32 v3, v0, s5
	v_lshrrev_b32_e32 v7, 31, v3
	v_ashrrev_i32_e32 v3, 1, v3
	v_add_u32_e32 v7, v3, v7
	v_mul_lo_u32 v3, v7, s4
	v_add_u32_e32 v101, 0, v3
	v_mul_lo_u32 v3, v7, 12
	v_sub_u32_e32 v0, v0, v3
	v_cmp_lt_i32_e32 vcc, v130, v131
	v_lshlrev_b32_e32 v102, 4, v0
	v_lshlrev_b32_e32 v82, 3, v0
	v_cndmask_b32_e32 v0, v229, v130, vcc
	v_lshlrev_b32_e32 v103, 2, v0
	v_xor_b32_e32 v0, 32, v229
	v_cmp_lt_i32_e32 vcc, v0, v131
	v_lshlrev_b32_e32 v100, 4, v2
	v_lshlrev_b32_e32 v80, 3, v2
	v_cndmask_b32_e32 v0, v229, v0, vcc
	v_mov_b64_e32 v[2:3], s[12:13]
	v_lshlrev_b32_e32 v104, 2, v0
	v_mad_i64_i32 v[2:3], s[4:5], v72, s70, v[2:3]
	v_lshlrev_b32_e32 v0, 4, v5
	v_lshl_add_u64 v[2:3], v[2:3], 0, v[0:1]
	s_mov_b64 s[4:5], 0x3291a000
	v_lshlrev_b32_e32 v74, 2, v5
	v_lshl_add_u64 v[84:85], v[2:3], 0, s[4:5]
	v_lshl_add_u64 v[2:3], s[8:9], 0, v[78:79]
	v_mov_b32_e32 v5, v1
	v_lshl_add_u64 v[86:87], v[2:3], 0, v[4:5]
	v_mov_b32_e32 v2, v1
	v_mov_b32_e32 v3, v1
	v_ashrrev_i32_e32 v73, 31, v72
	s_movk_i32 s4, 0x80
	s_movk_i32 s6, 0x7f
	v_mov_b32_e32 v0, v1
	v_mov_b32_e32 v4, 0
	v_mov_b64_e32 v[26:27], v[2:3]
	v_add_u32_e32 v95, 0x900, v94
	v_add_u32_e32 v96, 0x1200, v94
	v_add_u32_e32 v97, 0x1b00, v94
	v_ashrrev_i32_e32 v81, 31, v80
	v_ashrrev_i32_e32 v83, 31, v82
	v_cmp_gt_i32_e64 s[4:5], s4, v72
	v_cmp_lt_i32_e64 s[6:7], s6, v72
	v_mad_i64_i32 v[88:89], s[14:15], v6, s33, 0
	v_mad_i64_i32 v[90:91], s[14:15], v7, s33, 0
	v_lshlrev_b64 v[92:93], 10, v[72:73]
	v_add_u32_e32 v73, 64, v6
	v_add_u32_e32 v105, 64, v7
	s_mov_b32 s46, 0
	s_mov_b64 s[18:19], 0
	s_mov_b64 s[16:17], -1
	v_mov_b32_e32 v8, 0
	v_mov_b32_e32 v9, 0
	v_mov_b32_e32 v10, 0
	v_mov_b32_e32 v11, 0
	v_mov_b32_e32 v12, 0
	v_mov_b32_e32 v13, 0
	v_mov_b32_e32 v14, 0
	v_mov_b32_e32 v15, 0
	s_mov_b32 s48, s37
	v_mov_b64_e32 v[24:25], v[0:1]
	v_mov_b32_e32 v5, v4
	v_mov_b32_e32 v6, v4
	v_mov_b32_e32 v7, v4
	v_mov_b32_e32 v20, v4
	v_mov_b32_e32 v21, v4
	v_mov_b32_e32 v22, v4
	v_mov_b32_e32 v23, v4
	v_mov_b32_e32 v16, v4
	v_mov_b32_e32 v17, v4
	v_mov_b32_e32 v18, v4
	v_mov_b32_e32 v19, v4
	s_branch .LBB0_1745

.LBB0_1764:
	s_or_b64 exec, exec, s[18:19]
	s_waitcnt vmcnt(0)
	ds_write_b64 v98, v[24:25] offset:13312
	ds_write_b64 v98, v[26:27] offset:13328
	s_waitcnt lgkmcnt(0)
	s_barrier
	s_and_saveexec_b64 s[18:19], s[0:1]
	s_cbranch_execz .LBB0_1766
	v_add_u32_e32 v8, s50, v73
	v_mad_i64_i32 v[8:9], s[52:53], v8, s33, v[60:61]
	global_load_dwordx4 v[8:11], v[8:9], off

.LBB0_1771:
	s_nop 2
	v_max_f32_e32 v64, v57, v57
	v_max_f32_e32 v65, v56, v56
	v_max_f32_e32 v64, v65, v64
	v_max_f32_e32 v65, v59, v59
	v_max_f32_e32 v66, v58, v58
	v_max_f32_e32 v65, v66, v65
	v_max3_f32 v64, v64, v65, s76
	v_max_f32_e32 v65, v53, v53
	v_max_f32_e32 v66, v52, v52
	v_max_f32_e32 v65, v66, v65
	v_max_f32_e32 v66, v55, v55
	v_max_f32_e32 v67, v54, v54
	v_max_f32_e32 v66, v67, v66
	v_max3_f32 v64, v65, v66, v64
	v_max_f32_e32 v65, v49, v49
	v_max_f32_e32 v66, v48, v48
	v_max_f32_e32 v65, v66, v65
	v_max_f32_e32 v66, v51, v51
	v_max_f32_e32 v67, v50, v50
	v_max_f32_e32 v66, v67, v66
	v_max3_f32 v64, v65, v66, v64
	v_max_f32_e32 v65, v45, v45
	v_max_f32_e32 v66, v44, v44
	v_max_f32_e32 v65, v66, v65
	v_max_f32_e32 v66, v47, v47
	v_max_f32_e32 v67, v46, v46
	v_max_f32_e32 v66, v67, v66
	v_max3_f32 v64, v65, v66, v64
	ds_bpermute_b32 v65, v103, v64
	v_add_u32_e32 v114, 0x3000, v94
	v_add_u32_e32 v115, 0x3000, v95
	v_add_u32_e32 v116, 0x3000, v96
	v_add_u32_e32 v117, 0x3000, v97
	s_waitcnt lgkmcnt(0)
	v_max_f32_e32 v65, v65, v65
	v_max_f32_e32 v64, v64, v65
	ds_bpermute_b32 v65, v104, v64
	s_waitcnt lgkmcnt(0)
	v_max3_f32 v69, v107, v64, v65
	v_sub_f32_e32 v56, v56, v69
	v_exp_f32_e32 v56, v56
	v_sub_f32_e32 v57, v57, v69
	v_exp_f32_e32 v57, v57
	v_sub_f32_e32 v58, v58, v69
	v_exp_f32_e32 v58, v58
	v_sub_f32_e32 v59, v59, v69
	v_exp_f32_e32 v59, v59
	v_sub_f32_e32 v52, v52, v69
	v_add_f32_e32 v65, 0, v56
	v_exp_f32_e32 v52, v52
	v_sub_f32_e32 v53, v53, v69
	v_add_f32_e32 v65, v57, v65
	v_exp_f32_e32 v53, v53
	v_sub_f32_e32 v54, v54, v69
	v_add_f32_e32 v65, v58, v65
	v_exp_f32_e32 v54, v54
	v_sub_f32_e32 v55, v55, v69
	v_add_f32_e32 v65, v59, v65
	v_exp_f32_e32 v55, v55
	v_sub_f32_e32 v48, v48, v69
	v_add_f32_e32 v65, v52, v65
	v_exp_f32_e32 v70, v48
	v_sub_f32_e32 v49, v49, v69
	v_add_f32_e32 v65, v53, v65
	v_exp_f32_e32 v71, v49
	v_sub_f32_e32 v49, v50, v69
	v_sub_f32_e32 v64, v107, v69
	v_add_f32_e32 v65, v54, v65
	v_exp_f32_e32 v107, v49
	v_sub_f32_e32 v49, v51, v69
	v_add_f32_e32 v65, v55, v65
	v_exp_f32_e32 v108, v49
	v_sub_f32_e32 v44, v44, v69
	v_add_f32_e32 v48, v70, v65
	v_exp_f32_e32 v109, v44
	v_sub_f32_e32 v44, v45, v69
	v_add_f32_e32 v48, v71, v48
	v_exp_f32_e32 v110, v44
	v_sub_f32_e32 v44, v46, v69
	v_add_f32_e32 v48, v107, v48
	v_exp_f32_e32 v111, v44
	v_sub_f32_e32 v44, v47, v69
	v_add_f32_e32 v48, v108, v48
	v_exp_f32_e32 v112, v44
	v_add_f32_e32 v44, v109, v48
	v_add_f32_e32 v44, v110, v44
	v_exp_f32_e32 v68, v64
	v_add_f32_e32 v44, v111, v44
	v_add_f32_e32 v113, v112, v44
	v_cvt_pk_bf16_f32 v44, v56, v57
	v_cvt_pk_bf16_f32 v45, v58, v59
	v_cvt_pk_bf16_f32 v46, v52, v53
	v_cvt_pk_bf16_f32 v47, v54, v55
	ds_read_b128 v[48:51], v114 offset:1024
	ds_read_b128 v[52:55], v115 offset:1024
	ds_read_b128 v[56:59], v116 offset:1024
	ds_read_b128 v[64:67], v117 offset:1024
	v_pk_mul_f32 v[38:39], v[38:39], v[68:69] op_sel_hi:[1,0]
	v_pk_mul_f32 v[36:37], v[36:37], v[68:69] op_sel_hi:[1,0]
	v_pk_mul_f32 v[34:35], v[34:35], v[68:69] op_sel_hi:[1,0]
	v_pk_mul_f32 v[32:33], v[32:33], v[68:69] op_sel_hi:[1,0]
	v_pk_mul_f32 v[30:31], v[30:31], v[68:69] op_sel_hi:[1,0]
	v_pk_mul_f32 v[28:29], v[28:29], v[68:69] op_sel_hi:[1,0]
	v_pk_mul_f32 v[42:43], v[42:43], v[68:69] op_sel_hi:[1,0]
	v_pk_mul_f32 v[40:41], v[40:41], v[68:69] op_sel_hi:[1,0]
	s_waitcnt lgkmcnt(3)
	v_mfma_f32_16x16x32_bf16 v[36:39], v[48:51], v[44:47], v[36:39]
	s_waitcnt lgkmcnt(2)
	v_mfma_f32_16x16x32_bf16 v[32:35], v[52:55], v[44:47], v[32:35]
	s_waitcnt lgkmcnt(1)
	v_mfma_f32_16x16x32_bf16 v[28:31], v[56:59], v[44:47], v[28:31]
	s_waitcnt lgkmcnt(0)
	v_mfma_f32_16x16x32_bf16 v[40:43], v[64:67], v[44:47], v[40:43]
	ds_read_b128 v[48:51], v114 offset:1088
	ds_read_b128 v[52:55], v115 offset:1088
	ds_read_b128 v[56:59], v116 offset:1088
	ds_read_b128 v[64:67], v117 offset:1088
	v_cvt_pk_bf16_f32 v44, v70, v71
	v_cvt_pk_bf16_f32 v45, v107, v108
	v_cvt_pk_bf16_f32 v46, v109, v110
	v_cvt_pk_bf16_f32 v47, v111, v112
	s_waitcnt lgkmcnt(3)
	v_mfma_f32_16x16x32_bf16 v[36:39], v[48:51], v[44:47], v[36:39]
	v_fmac_f32_e32 v113, v0, v68
	v_mov_b32_e32 v107, v69
	v_mov_b32_e32 v0, v113
	s_waitcnt lgkmcnt(2)
	v_mfma_f32_16x16x32_bf16 v[32:35], v[52:55], v[44:47], v[32:35]
	s_waitcnt lgkmcnt(1)
	v_mfma_f32_16x16x32_bf16 v[28:31], v[56:59], v[44:47], v[28:31]
	s_waitcnt lgkmcnt(0)
	v_mfma_f32_16x16x32_bf16 v[40:43], v[64:67], v[44:47], v[40:43]

.LBB0_1778:
	s_or_b64 exec, exec, s[18:19]
	s_add_i32 s50, s46, 1
	s_and_b64 s[16:17], s[16:17], exec
	s_mul_i32 s51, s50, s39
	s_cselect_b32 s16, s40, s37
	s_add_i32 s16, s51, s16
	s_cmpk_lt_i32 s16, 0x400
	s_cselect_b64 s[18:19], -1, 0
	s_cmpk_gt_i32 s16, 0x3ff
	s_waitcnt vmcnt(0)
	ds_write_b64 v98, v[24:25] offset:13312
	ds_write_b64 v98, v[26:27] offset:13328
	s_waitcnt lgkmcnt(0)
	s_barrier
	s_cbranch_scc1 .LBB0_1790
	s_and_b64 s[20:21], s[18:19], exec
	s_cselect_b32 s48, s16, s48
	s_and_b32 s52, s48, 63
	s_mul_i32 s16, s52, 0x60000
	s_add_u32 s16, s41, s16
	s_addc_u32 s17, s42, 0
	s_and_saveexec_b64 s[20:21], s[0:1]
	s_cbranch_execz .LBB0_1781
	v_lshl_add_u64 v[2:3], s[16:17], 0, v[88:89]
	v_lshl_add_u64 v[2:3], v[80:81], 1, v[2:3]
	global_load_dwordx4 v[8:11], v[2:3], off

.LBB0_1793:
	s_nop 2
	v_max_f32_e32 v2, v69, v69
	v_max_f32_e32 v3, v68, v68
	v_max_f32_e32 v2, v3, v2
	v_max_f32_e32 v3, v71, v71
	v_max_f32_e32 v106, v70, v70
	v_max_f32_e32 v3, v106, v3
	v_max3_f32 v2, v2, v3, s76
	v_max_f32_e32 v3, v65, v65
	v_max_f32_e32 v106, v64, v64
	v_max_f32_e32 v3, v106, v3
	v_max_f32_e32 v106, v67, v67
	v_max_f32_e32 v108, v66, v66
	v_max_f32_e32 v106, v108, v106
	v_max3_f32 v2, v3, v106, v2
	v_max_f32_e32 v3, v61, v61
	v_max_f32_e32 v106, v60, v60
	v_max_f32_e32 v3, v106, v3
	v_max_f32_e32 v106, v63, v63
	v_max_f32_e32 v108, v62, v62
	v_max_f32_e32 v106, v108, v106
	v_max3_f32 v2, v3, v106, v2
	v_max_f32_e32 v3, v57, v57
	v_max_f32_e32 v106, v56, v56
	v_max_f32_e32 v3, v106, v3
	v_max_f32_e32 v106, v59, v59
	v_max_f32_e32 v108, v58, v58
	v_max_f32_e32 v106, v108, v106
	v_max3_f32 v2, v3, v106, v2
	ds_bpermute_b32 v3, v103, v2
	v_add_u32_e32 v118, 0x3000, v94
	v_add_u32_e32 v119, 0x3000, v95
	v_add_u32_e32 v120, 0x3000, v96
	v_add_u32_e32 v121, 0x3000, v97
	s_waitcnt lgkmcnt(0)
	v_max_f32_e32 v3, v3, v3
	v_max_f32_e32 v2, v2, v3
	ds_bpermute_b32 v3, v104, v2
	s_waitcnt lgkmcnt(0)
	v_max3_f32 v2, v107, v2, v3
	v_sub_f32_e32 v68, v68, v2
	v_exp_f32_e32 v68, v68
	v_sub_f32_e32 v69, v69, v2
	v_exp_f32_e32 v69, v69
	v_sub_f32_e32 v70, v70, v2
	v_exp_f32_e32 v70, v70
	v_sub_f32_e32 v71, v71, v2
	v_exp_f32_e32 v71, v71
	v_sub_f32_e32 v64, v64, v2
	v_add_f32_e32 v106, 0, v68
	v_exp_f32_e32 v64, v64
	v_sub_f32_e32 v65, v65, v2
	v_add_f32_e32 v106, v69, v106
	v_exp_f32_e32 v65, v65
	v_sub_f32_e32 v66, v66, v2
	v_add_f32_e32 v106, v70, v106
	v_exp_f32_e32 v66, v66
	v_sub_f32_e32 v67, v67, v2
	v_add_f32_e32 v106, v71, v106
	v_exp_f32_e32 v67, v67
	v_sub_f32_e32 v60, v60, v2
	v_add_f32_e32 v106, v64, v106
	v_exp_f32_e32 v110, v60
	v_sub_f32_e32 v61, v61, v2
	v_add_f32_e32 v106, v65, v106
	v_exp_f32_e32 v111, v61
	v_sub_f32_e32 v61, v62, v2
	v_sub_f32_e32 v56, v56, v2
	v_add_f32_e32 v106, v66, v106
	v_exp_f32_e32 v112, v61
	v_sub_f32_e32 v61, v63, v2
	v_exp_f32_e32 v114, v56
	v_sub_f32_e32 v56, v57, v2
	v_sub_f32_e32 v3, v107, v2
	v_add_f32_e32 v106, v67, v106
	v_exp_f32_e32 v113, v61
	v_exp_f32_e32 v115, v56
	v_sub_f32_e32 v56, v58, v2
	v_sub_f32_e32 v2, v59, v2
	v_add_f32_e32 v60, v110, v106
	v_exp_f32_e32 v117, v2
	v_exp_f32_e32 v2, v3
	v_add_f32_e32 v60, v111, v60
	v_add_f32_e32 v60, v112, v60
	v_add_f32_e32 v60, v113, v60
	v_exp_f32_e32 v116, v56
	v_pk_mul_f32 v[38:39], v[38:39], v[2:3] op_sel_hi:[1,0]
	v_pk_mul_f32 v[36:37], v[36:37], v[2:3] op_sel_hi:[1,0]
	v_pk_mul_f32 v[34:35], v[34:35], v[2:3] op_sel_hi:[1,0]
	v_pk_mul_f32 v[32:33], v[32:33], v[2:3] op_sel_hi:[1,0]
	v_pk_mul_f32 v[30:31], v[30:31], v[2:3] op_sel_hi:[1,0]
	v_pk_mul_f32 v[28:29], v[28:29], v[2:3] op_sel_hi:[1,0]
	v_pk_mul_f32 v[42:43], v[42:43], v[2:3] op_sel_hi:[1,0]
	v_pk_mul_f32 v[40:41], v[40:41], v[2:3] op_sel_hi:[1,0]
	v_add_f32_e32 v3, v114, v60
	v_cvt_pk_bf16_f32 v56, v68, v69
	v_cvt_pk_bf16_f32 v57, v70, v71
	v_cvt_pk_bf16_f32 v58, v64, v65
	v_cvt_pk_bf16_f32 v59, v66, v67
	ds_read_b128 v[60:63], v118 offset:1024
	ds_read_b128 v[64:67], v119 offset:1024
	ds_read_b128 v[68:71], v120 offset:1024
	ds_read_b128 v[106:109], v121 offset:1024
	v_add_f32_e32 v3, v115, v3
	v_add_f32_e32 v3, v116, v3
	v_add_f32_e32 v3, v117, v3
	s_waitcnt lgkmcnt(3)
	v_mfma_f32_16x16x32_bf16 v[36:39], v[60:63], v[56:59], v[36:39]
	s_waitcnt lgkmcnt(2)
	v_mfma_f32_16x16x32_bf16 v[32:35], v[64:67], v[56:59], v[32:35]
	s_waitcnt lgkmcnt(1)
	v_mfma_f32_16x16x32_bf16 v[28:31], v[68:71], v[56:59], v[28:31]
	s_waitcnt lgkmcnt(0)
	v_mfma_f32_16x16x32_bf16 v[40:43], v[106:109], v[56:59], v[40:43]
	ds_read_b128 v[60:63], v118 offset:1088
	ds_read_b128 v[64:67], v119 offset:1088
	ds_read_b128 v[68:71], v120 offset:1088
	ds_read_b128 v[106:109], v121 offset:1088
	v_cvt_pk_bf16_f32 v56, v110, v111
	v_cvt_pk_bf16_f32 v57, v112, v113
	v_cvt_pk_bf16_f32 v58, v114, v115
	v_cvt_pk_bf16_f32 v59, v116, v117
	s_waitcnt lgkmcnt(3)
	v_mfma_f32_16x16x32_bf16 v[36:39], v[60:63], v[56:59], v[36:39]
	v_fmac_f32_e32 v3, v0, v2
	v_mov_b32_e32 v0, v3
	s_waitcnt lgkmcnt(2)
	v_mfma_f32_16x16x32_bf16 v[32:35], v[64:67], v[56:59], v[32:35]
	s_waitcnt lgkmcnt(1)
	v_mfma_f32_16x16x32_bf16 v[28:31], v[68:71], v[56:59], v[28:31]
	s_waitcnt lgkmcnt(0)
	v_mfma_f32_16x16x32_bf16 v[40:43], v[106:109], v[56:59], v[40:43]
